# v004 plus a short s_sleep 3 for waves 4-7 at the start of each QK^T block (de-phases the two waves of a SIMD)
# baseline (speedup 1.0000x reference)
.LBB0_394:
	s_sub_i32 s10, s54, 63
	s_cmp_le_i32 s10, s5
	s_cselect_b64 s[76:77], -1, 0
	s_cmp_gt_i32 s10, s5
	s_cbranch_scc1 .LBB0_396
	s_cmp_lt_u32 s96, 4
	s_cbranch_scc1 .Lstg_h1
	s_sleep 3
.Lstg_h1:
	ds_read_b128 v[236:239], v196 offset:57344
	ds_read_b128 v[240:243], v207 offset:12288
	ds_read_b128 v[246:249], v197 offset:57344
	ds_read_b128 v[250:253], v205 offset:12288
	ds_read_b128 v[6:9], v195
	ds_read_b128 v[10:13], v195 offset:1024
	ds_read_b128 v[2:5], v195 offset:2048
	v_cvt_pk_bf16_f32 v18, v224, v226
	v_cvt_pk_bf16_f32 v19, v222, v225
	v_cvt_pk_bf16_f32 v20, v220, v223
	v_cvt_pk_bf16_f32 v21, v219, v221
	v_cvt_pk_bf16_f32 v22, v216, v218
	v_cvt_pk_bf16_f32 v23, v214, v217
	v_cvt_pk_bf16_f32 v24, v212, v215
	v_cvt_pk_bf16_f32 v25, v211, v213
	v_add_f32_e32 v0, 0, v224
	v_add_f32_e32 v0, v226, v0
	v_add_f32_e32 v0, v222, v0
	v_add_f32_e32 v0, v225, v0
	v_add_f32_e32 v0, v220, v0
	v_add_f32_e32 v0, v223, v0
	v_add_f32_e32 v0, v219, v0
	v_add_f32_e32 v0, v221, v0
	s_waitcnt lgkmcnt(6)
	v_mfma_f32_32x32x16_bf16 v[112:127], v[236:239], v[156:159], 0
	ds_read_b128 v[236:239], v199 offset:57344
	v_add_f32_e32 v0, v216, v0
	v_add_f32_e32 v0, v218, v0
	v_permlane32_swap_b32_e32 v18, v20
	s_waitcnt lgkmcnt(6)
	v_mfma_f32_32x32x16_bf16 v[96:111], v[240:243], v[156:159], 0
	ds_read_b128 v[240:243], v206 offset:12288
	v_add_f32_e32 v0, v214, v0
	v_add_f32_e32 v0, v217, v0
	v_permlane32_swap_b32_e32 v19, v21
	s_waitcnt lgkmcnt(6)
	v_mfma_f32_32x32x16_bf16 v[112:127], v[246:249], v[152:155], v[112:127]
	ds_read_b128 v[246:249], v198 offset:57344
	v_add_f32_e32 v0, v212, v0
	v_add_f32_e32 v0, v215, v0
	s_waitcnt lgkmcnt(6)
	v_mfma_f32_32x32x16_bf16 v[96:111], v[250:253], v[152:155], v[96:111]
	ds_read_b128 v[250:253], v204 offset:12288
	v_permlane32_swap_b32_e32 v22, v24
	v_add_f32_e32 v0, v211, v0
	s_waitcnt lgkmcnt(3)
	v_mfma_f32_32x32x16_bf16 v[112:127], v[236:239], v[148:151], v[112:127]
	ds_read_b128 v[236:239], v196 offset:57472
	v_add_f32_e32 v0, v213, v0
	v_permlane32_swap_b32_e32 v23, v25
	s_waitcnt lgkmcnt(3)
	v_mfma_f32_32x32x16_bf16 v[96:111], v[240:243], v[148:151], v[96:111]
	ds_read_b128 v[240:243], v207 offset:12416
	v_exp_f32_e32 v182, v182
	v_exp_f32_e32 v183, v183
	s_waitcnt lgkmcnt(3)
	v_mfma_f32_32x32x16_bf16 v[112:127], v[246:249], v[144:147], v[112:127]
	ds_read_b128 v[246:249], v197 offset:57472
	v_exp_f32_e32 v180, v180
	v_exp_f32_e32 v181, v181
	s_waitcnt lgkmcnt(3)
	v_mfma_f32_32x32x16_bf16 v[96:111], v[250:253], v[144:147], v[96:111]
	ds_read_b128 v[250:253], v205 offset:12416
	v_add_f32_e32 v0, v182, v0
	v_exp_f32_e32 v170, v170
	s_waitcnt lgkmcnt(3)
	v_mfma_f32_32x32x16_bf16 v[112:127], v[236:239], v[140:143], v[112:127]
	ds_read_b128 v[236:239], v199 offset:57472
	v_add_f32_e32 v0, v183, v0
	v_exp_f32_e32 v171, v171
	s_waitcnt lgkmcnt(3)
	v_mfma_f32_32x32x16_bf16 v[96:111], v[240:243], v[140:143], v[96:111]
	ds_read_b128 v[240:243], v206 offset:12416
	v_add_f32_e32 v0, v180, v0
	v_exp_f32_e32 v168, v168
	s_waitcnt lgkmcnt(3)
	v_mfma_f32_32x32x16_bf16 v[112:127], v[246:249], v[136:139], v[112:127]
	ds_read_b128 v[246:249], v198 offset:57472
	v_add_f32_e32 v0, v181, v0
	v_exp_f32_e32 v169, v169
	s_waitcnt lgkmcnt(3)
	v_mfma_f32_32x32x16_bf16 v[96:111], v[250:253], v[136:139], v[96:111]
	ds_read_b128 v[250:253], v204 offset:12416
	v_cvt_pk_bf16_f32 v26, v182, v183
	v_cvt_pk_bf16_f32 v27, v180, v181
	s_waitcnt lgkmcnt(3)
	v_mfma_f32_32x32x16_bf16 v[112:127], v[236:239], v[132:135], v[112:127]
	ds_read_b128 v[236:239], v196 offset:57600
	v_add_f32_e32 v0, v170, v0
	v_exp_f32_e32 v166, v166
	s_waitcnt lgkmcnt(3)
	v_mfma_f32_32x32x16_bf16 v[96:111], v[240:243], v[132:135], v[96:111]
	ds_read_b128 v[240:243], v207 offset:12544
	v_add_f32_e32 v0, v171, v0
	v_exp_f32_e32 v167, v167
	s_waitcnt lgkmcnt(3)
	v_mfma_f32_32x32x16_bf16 v[112:127], v[246:249], v[128:131], v[112:127]
	ds_read_b128 v[246:249], v197 offset:57600
	v_add_f32_e32 v0, v168, v0
	v_exp_f32_e32 v164, v164
	s_waitcnt lgkmcnt(3)
	v_mfma_f32_32x32x16_bf16 v[96:111], v[250:253], v[128:131], v[96:111]
	ds_read_b128 v[250:253], v205 offset:12544
	v_add_f32_e32 v0, v169, v0
	v_exp_f32_e32 v165, v165
	s_waitcnt lgkmcnt(3)
	v_mfma_f32_32x32x16_bf16 v[112:127], v[236:239], v[6:9], v[112:127]
	ds_read_b128 v[236:239], v199 offset:57600
	v_cvt_pk_bf16_f32 v28, v170, v171
	v_cvt_pk_bf16_f32 v29, v168, v169
	s_waitcnt lgkmcnt(3)
	v_mfma_f32_32x32x16_bf16 v[96:111], v[240:243], v[6:9], v[96:111]
	ds_read_b128 v[240:243], v206 offset:12544
	ds_read_b128 v[6:9], v195 offset:3072
	v_add_f32_e32 v0, v166, v0
	v_exp_f32_e32 v162, v162
	s_waitcnt lgkmcnt(4)
	v_mfma_f32_32x32x16_bf16 v[112:127], v[246:249], v[10:13], v[112:127]
	ds_read_b128 v[246:249], v198 offset:57600
	v_permlane32_swap_b32_e32 v26, v28
	v_permlane32_swap_b32_e32 v27, v29
	s_waitcnt lgkmcnt(4)
	v_mfma_f32_32x32x16_bf16 v[96:111], v[250:253], v[10:13], v[96:111]
	ds_read_b128 v[250:253], v204 offset:12544
	v_add_f32_e32 v0, v167, v0
	v_exp_f32_e32 v163, v163
	s_waitcnt lgkmcnt(4)
	v_mfma_f32_32x32x16_bf16 v[112:127], v[236:239], v[2:5], v[112:127]
	v_add_f32_e32 v0, v164, v0
	v_exp_f32_e32 v160, v160
	s_waitcnt lgkmcnt(3)
	v_mfma_f32_32x32x16_bf16 v[96:111], v[240:243], v[2:5], v[96:111]
	v_add_f32_e32 v0, v165, v0
	v_exp_f32_e32 v161, v161
	s_waitcnt lgkmcnt(1)
	v_mfma_f32_32x32x16_bf16 v[112:127], v[246:249], v[6:9], v[112:127]
	v_cvt_pk_bf16_f32 v168, v166, v167
	v_cvt_pk_bf16_f32 v169, v164, v165
	s_waitcnt lgkmcnt(0)
	v_mfma_f32_32x32x16_bf16 v[96:111], v[250:253], v[6:9], v[96:111]
	v_add_f32_e32 v0, v162, v0
	v_add_f32_e32 v0, v163, v0
	v_add_f32_e32 v0, v160, v0
	v_add_f32_e32 v0, v161, v0
	v_cvt_pk_bf16_f32 v170, v162, v163
	v_cvt_pk_bf16_f32 v171, v160, v161
	v_mov_b32_e32 v14, v0
	s_nop 1
	v_permlane32_swap_b32_e32 v168, v170
	v_permlane32_swap_b32_e32 v169, v171
	v_permlane32_swap_b32_e32 v0, v14
	s_branch .Lattn_h1_join

.LBB0_405:
	v_cndmask_b32_e64 v180, v17, v208, s[10:11]
	v_mul_f32_e32 v219, 0xbdd53b94, v180
	v_fmamk_f32 v17, v112, 0x3dd53b94, v219
	v_fmamk_f32 v18, v113, 0x3dd53b94, v219
	v_fmamk_f32 v19, v114, 0x3dd53b94, v219
	v_fmamk_f32 v20, v115, 0x3dd53b94, v219
	v_fmamk_f32 v21, v116, 0x3dd53b94, v219
	v_fmamk_f32 v22, v117, 0x3dd53b94, v219
	v_fmamk_f32 v23, v118, 0x3dd53b94, v219
	v_fmamk_f32 v24, v119, 0x3dd53b94, v219
	v_fmamk_f32 v25, v120, 0x3dd53b94, v219
	v_fmamk_f32 v26, v121, 0x3dd53b94, v219
	v_fmamk_f32 v27, v122, 0x3dd53b94, v219
	v_fmamk_f32 v28, v123, 0x3dd53b94, v219
	v_fmamk_f32 v29, v124, 0x3dd53b94, v219
	v_fmamk_f32 v30, v125, 0x3dd53b94, v219
	v_fmamk_f32 v31, v126, 0x3dd53b94, v219
	v_fmamk_f32 v112, v127, 0x3dd53b94, v219
	v_exp_f32_e32 v216, v17
	v_exp_f32_e32 v218, v18
	v_exp_f32_e32 v214, v19
	v_exp_f32_e32 v217, v20
	v_exp_f32_e32 v212, v21
	v_exp_f32_e32 v215, v22
	v_exp_f32_e32 v211, v23
	v_exp_f32_e32 v213, v24
	v_exp_f32_e32 v182, v25
	v_exp_f32_e32 v208, v26
	v_exp_f32_e32 v171, v27
	v_exp_f32_e32 v183, v28
	v_exp_f32_e32 v169, v29
	v_exp_f32_e32 v181, v30
	v_exp_f32_e32 v168, v31
	v_exp_f32_e32 v170, v112
	v_fmamk_f32 v220, v96, 0x3dd53b94, v219
	v_fmamk_f32 v221, v97, 0x3dd53b94, v219
	v_fmamk_f32 v222, v98, 0x3dd53b94, v219
	v_fmamk_f32 v223, v99, 0x3dd53b94, v219
	v_fmamk_f32 v224, v100, 0x3dd53b94, v219
	v_fmamk_f32 v225, v101, 0x3dd53b94, v219
	v_fmamk_f32 v226, v102, 0x3dd53b94, v219
	v_fmamk_f32 v227, v103, 0x3dd53b94, v219
	v_fmamk_f32 v228, v104, 0x3dd53b94, v219
	v_fmamk_f32 v229, v105, 0x3dd53b94, v219
	v_fmamk_f32 v230, v106, 0x3dd53b94, v219
	v_fmamk_f32 v231, v107, 0x3dd53b94, v219
	v_fmamk_f32 v232, v108, 0x3dd53b94, v219
	v_fmamk_f32 v233, v109, 0x3dd53b94, v219
	v_fmamk_f32 v234, v110, 0x3dd53b94, v219
	v_fmac_f32_e32 v219, 0x3dd53b94, v111
	s_add_i32 s10, s54, 1
	s_waitcnt lgkmcnt(0)
	s_barrier
	s_cmp_gt_i32 s10, s5
	s_cbranch_scc1 .LBB0_407
	s_cmp_lt_u32 s96, 4
	s_cbranch_scc1 .Lstg_h2
	s_sleep 3
.Lstg_h2:
	ds_read_b128 v[236:239], v196 offset:32768
	ds_read_b128 v[240:243], v196 offset:45056
	ds_read_b128 v[246:249], v197 offset:32768
	ds_read_b128 v[250:253], v197 offset:45056
	ds_read_b128 v[6:9], v195
	ds_read_b128 v[10:13], v195 offset:1024
	ds_read_b128 v[2:5], v195 offset:2048
	v_cvt_pk_bf16_f32 v18, v216, v218
	v_cvt_pk_bf16_f32 v19, v214, v217
	v_cvt_pk_bf16_f32 v20, v212, v215
	v_cvt_pk_bf16_f32 v21, v211, v213
	v_cvt_pk_bf16_f32 v22, v182, v208
	v_cvt_pk_bf16_f32 v23, v171, v183
	v_cvt_pk_bf16_f32 v24, v169, v181
	v_cvt_pk_bf16_f32 v25, v168, v170
	v_add_f32_e32 v17, 0, v216
	v_add_f32_e32 v17, v218, v17
	v_add_f32_e32 v17, v214, v17
	v_add_f32_e32 v17, v217, v17
	v_add_f32_e32 v17, v212, v17
	v_add_f32_e32 v17, v215, v17
	v_add_f32_e32 v17, v211, v17
	v_add_f32_e32 v17, v213, v17
	s_waitcnt lgkmcnt(6)
	v_mfma_f32_32x32x16_bf16 v[112:127], v[236:239], v[156:159], 0
	ds_read_b128 v[236:239], v199 offset:32768
	v_add_f32_e32 v17, v182, v17
	v_add_f32_e32 v17, v208, v17
	v_permlane32_swap_b32_e32 v18, v20
	s_waitcnt lgkmcnt(6)
	v_mfma_f32_32x32x16_bf16 v[96:111], v[240:243], v[156:159], 0
	ds_read_b128 v[240:243], v199 offset:45056
	v_add_f32_e32 v17, v171, v17
	v_add_f32_e32 v17, v183, v17
	v_permlane32_swap_b32_e32 v19, v21
	s_waitcnt lgkmcnt(6)
	v_mfma_f32_32x32x16_bf16 v[112:127], v[246:249], v[152:155], v[112:127]
	ds_read_b128 v[246:249], v198 offset:32768
	v_add_f32_e32 v17, v169, v17
	v_add_f32_e32 v17, v181, v17
	s_waitcnt lgkmcnt(6)
	v_mfma_f32_32x32x16_bf16 v[96:111], v[250:253], v[152:155], v[96:111]
	ds_read_b128 v[250:253], v198 offset:45056
	v_permlane32_swap_b32_e32 v22, v24
	v_add_f32_e32 v17, v168, v17
	s_waitcnt lgkmcnt(3)
	v_mfma_f32_32x32x16_bf16 v[112:127], v[236:239], v[148:151], v[112:127]
	ds_read_b128 v[236:239], v196 offset:32896
	v_add_f32_e32 v17, v170, v17
	v_permlane32_swap_b32_e32 v23, v25
	s_waitcnt lgkmcnt(3)
	v_mfma_f32_32x32x16_bf16 v[96:111], v[240:243], v[148:151], v[96:111]
	ds_read_b128 v[240:243], v196 offset:45184
	v_exp_f32_e32 v220, v220
	v_exp_f32_e32 v221, v221
	s_waitcnt lgkmcnt(3)
	v_mfma_f32_32x32x16_bf16 v[112:127], v[246:249], v[144:147], v[112:127]
	ds_read_b128 v[246:249], v197 offset:32896
	v_exp_f32_e32 v222, v222
	v_exp_f32_e32 v223, v223
	s_waitcnt lgkmcnt(3)
	v_mfma_f32_32x32x16_bf16 v[96:111], v[250:253], v[144:147], v[96:111]
	ds_read_b128 v[250:253], v197 offset:45184
	v_add_f32_e32 v17, v220, v17
	v_exp_f32_e32 v224, v224
	s_waitcnt lgkmcnt(3)
	v_mfma_f32_32x32x16_bf16 v[112:127], v[236:239], v[140:143], v[112:127]
	ds_read_b128 v[236:239], v199 offset:32896
	v_add_f32_e32 v17, v221, v17
	v_exp_f32_e32 v225, v225
	s_waitcnt lgkmcnt(3)
	v_mfma_f32_32x32x16_bf16 v[96:111], v[240:243], v[140:143], v[96:111]
	ds_read_b128 v[240:243], v199 offset:45184
	v_add_f32_e32 v17, v222, v17
	v_exp_f32_e32 v226, v226
	s_waitcnt lgkmcnt(3)
	v_mfma_f32_32x32x16_bf16 v[112:127], v[246:249], v[136:139], v[112:127]
	ds_read_b128 v[246:249], v198 offset:32896
	v_add_f32_e32 v17, v223, v17
	v_exp_f32_e32 v227, v227
	s_waitcnt lgkmcnt(3)
	v_mfma_f32_32x32x16_bf16 v[96:111], v[250:253], v[136:139], v[96:111]
	ds_read_b128 v[250:253], v198 offset:45184
	v_cvt_pk_bf16_f32 v26, v220, v221
	v_cvt_pk_bf16_f32 v27, v222, v223
	s_waitcnt lgkmcnt(3)
	v_mfma_f32_32x32x16_bf16 v[112:127], v[236:239], v[132:135], v[112:127]
	ds_read_b128 v[236:239], v196 offset:33024
	v_add_f32_e32 v17, v224, v17
	v_exp_f32_e32 v228, v228
	s_waitcnt lgkmcnt(3)
	v_mfma_f32_32x32x16_bf16 v[96:111], v[240:243], v[132:135], v[96:111]
	ds_read_b128 v[240:243], v196 offset:45312
	v_add_f32_e32 v17, v225, v17
	v_exp_f32_e32 v229, v229
	s_waitcnt lgkmcnt(3)
	v_mfma_f32_32x32x16_bf16 v[112:127], v[246:249], v[128:131], v[112:127]
	ds_read_b128 v[246:249], v197 offset:33024
	v_add_f32_e32 v17, v226, v17
	v_exp_f32_e32 v230, v230
	s_waitcnt lgkmcnt(3)
	v_mfma_f32_32x32x16_bf16 v[96:111], v[250:253], v[128:131], v[96:111]
	ds_read_b128 v[250:253], v197 offset:45312
	v_add_f32_e32 v17, v227, v17
	v_exp_f32_e32 v231, v231
	s_waitcnt lgkmcnt(3)
	v_mfma_f32_32x32x16_bf16 v[112:127], v[236:239], v[6:9], v[112:127]
	ds_read_b128 v[236:239], v199 offset:33024
	v_cvt_pk_bf16_f32 v28, v224, v225
	v_cvt_pk_bf16_f32 v29, v226, v227
	s_waitcnt lgkmcnt(3)
	v_mfma_f32_32x32x16_bf16 v[96:111], v[240:243], v[6:9], v[96:111]
	ds_read_b128 v[240:243], v199 offset:45312
	ds_read_b128 v[6:9], v195 offset:3072
	v_add_f32_e32 v17, v228, v17
	v_exp_f32_e32 v232, v232
	s_waitcnt lgkmcnt(4)
	v_mfma_f32_32x32x16_bf16 v[112:127], v[246:249], v[10:13], v[112:127]
	ds_read_b128 v[246:249], v198 offset:33024
	v_permlane32_swap_b32_e32 v26, v28
	v_permlane32_swap_b32_e32 v27, v29
	s_waitcnt lgkmcnt(4)
	v_mfma_f32_32x32x16_bf16 v[96:111], v[250:253], v[10:13], v[96:111]
	ds_read_b128 v[250:253], v198 offset:45312
	v_add_f32_e32 v17, v229, v17
	v_exp_f32_e32 v233, v233
	s_waitcnt lgkmcnt(4)
	v_mfma_f32_32x32x16_bf16 v[112:127], v[236:239], v[2:5], v[112:127]
	v_add_f32_e32 v17, v230, v17
	v_exp_f32_e32 v234, v234
	s_waitcnt lgkmcnt(3)
	v_mfma_f32_32x32x16_bf16 v[96:111], v[240:243], v[2:5], v[96:111]
	v_add_f32_e32 v17, v231, v17
	v_exp_f32_e32 v219, v219
	s_waitcnt lgkmcnt(1)
	v_mfma_f32_32x32x16_bf16 v[112:127], v[246:249], v[6:9], v[112:127]
	v_cvt_pk_bf16_f32 v168, v228, v229
	v_cvt_pk_bf16_f32 v169, v230, v231
	s_waitcnt lgkmcnt(0)
	v_mfma_f32_32x32x16_bf16 v[96:111], v[250:253], v[6:9], v[96:111]
	v_add_f32_e32 v17, v232, v17
	v_add_f32_e32 v17, v233, v17
	v_add_f32_e32 v17, v234, v17
	v_add_f32_e32 v17, v219, v17
	v_cvt_pk_bf16_f32 v170, v232, v233
	v_cvt_pk_bf16_f32 v171, v234, v219
	v_mov_b32_e32 v30, v17
	s_nop 1
	v_permlane32_swap_b32_e32 v168, v170
	v_permlane32_swap_b32_e32 v169, v171
	v_permlane32_swap_b32_e32 v17, v30
	s_branch .Lattn_h2_join
